# v26 + nt hint on P7 K-loop A-tile (ACT) LDS-DMA loads
# baseline (speedup 1.0000x reference)
; #define PG8_STAGE(bufoff, gbase, voff) do { _Pragma("unroll") for (int _i = 0; _i < 2; ++_i) \
;         __builtin_amdgcn_global_load_lds((const unsigned*)((const char*)(gbase) + (voff)[_i]), (PG8_LAS unsigned*)(lds + (bufoff) + ldsw + _i * 8192), 16, 0, 0); } while (0)
; #define PG8_LDA(dst, b, h) do { _Pragma("unroll") for (int m = 0; m < 4; ++m) _Pragma("unroll") for (int k = 0; k < 2; ++k) dst[m][k] = *(const PG8_LAS bf16x8*)(lds + PG8_SA(b, h) + aoff + m * 2048 + k * 1024); } while (0)
; #define PG8_LDB(dst, b, h) do { _Pragma("unroll") for (int n = 0; n < 2; ++n) _Pragma("unroll") for (int k = 0; k < 2; ++k) dst[n][k] = *(const PG8_LAS bf16x8*)(lds + PG8_SB(b, h) + boff + n * 2048 + k * 1024); } while (0)
; #define PG8_MMA(ai, bj, At, Bt) do { __builtin_amdgcn_s_setprio(1); _Pragma("unroll") for (int m = 0; m < 4; ++m) _Pragma("unroll") for (int n = 0; n < 2; ++n) _Pragma("unroll") for (int k = 0; k < 2; ++k) \
;         acc[ai][bj][m][n] = __builtin_amdgcn_mfma_f32_16x16x32_bf16(Bt[n][k], At[m][k], acc[ai][bj][m][n], 0, 0, 0); __builtin_amdgcn_s_setprio(0); } while (0)
; #define PG8_WAIT_V(n) asm volatile("s_waitcnt vmcnt(" #n ")" ::: "memory")
; #define PG8_WAIT_L(n) asm volatile("s_waitcnt lgkmcnt(" #n ")" ::: "memory")
; #define PG8_BAR __builtin_amdgcn_s_barrier()
; #define PG8_SCHED __builtin_amdgcn_sched_barrier(0)
; template <class Epi, class Sched, bool ALIGN_EPI = false, bool SP2 = false, bool AGM = false  >
; __device__ __forceinline__ void gemm_phase(PG8_LAS unsigned char* lds, const Gemm g, const Sched& S, const Epi& E) {
;     ...
;             if constexpr (SP2) {
;             PG8_LDB(B0, 0, 0); PG8_LDB(B1, 0, 1); PG8_SCHED; PG8_LDA(At, 0, 0); PG8_STAGE(PG8_SA(1, 1), a1 + hstepA, voffA);
;             PG8_WAIT_V(8); PG8_WAIT_L(0); PG8_BAR; PG8_MMA(0, 0, At, B0); PG8_MMA(0, 1, At, B1); PG8_BAR; PG8_SCHED;
;             PG8_LDA(At, 0, 1); PG8_STAGE(PG8_SB(0, 0), b2, voffB); PG8_STAGE(PG8_SB(0, 1), b2 + hstep, voffB); PG8_STAGE(PG8_SA(0, 0), a2, voffA);
;             PG8_WAIT_V(8); PG8_WAIT_L(0); PG8_BAR; PG8_MMA(1, 0, At, B0); PG8_MMA(1, 1, At, B1); PG8_BAR; PG8_SCHED;
;             PG8_LDB(B0, 1, 0); PG8_LDB(B1, 1, 1); PG8_SCHED; PG8_LDA(At, 1, 0); PG8_STAGE(PG8_SA(0, 1), a2 + hstepA, voffA);
.LBB0_1068:
	ds_read_b128 v[150:153], v167
	ds_read_b128 v[156:159], v167 offset:1024
	ds_read_b128 v[160:163], v167 offset:2048
	ds_read_b128 v[176:179], v167 offset:3072
	ds_read_b128 v[180:183], v168
	ds_read_b128 v[184:187], v168 offset:1024
	ds_read_b128 v[188:191], v168 offset:2048
	ds_read_b128 v[192:195], v168 offset:3072
	s_add_u32 s34, s30, 0xfff50080
	s_addc_u32 s35, s31, -1
	s_cmp_eq_u32 s65, 40
	s_cselect_b32 s37, s13, s35
	s_cselect_b32 s36, s12, s34
	s_cselect_b32 s35, s29, s33
	s_cselect_b32 s34, s28, s5
	v_lshl_add_u64 v[164:165], s[30:31], 0, v[142:143]
	s_add_i32 m0, s39, 0xc000
	ds_read_b128 v[196:199], v169
	ds_read_b128 v[200:203], v169 offset:1024
	ds_read_b128 v[204:207], v169 offset:2048
	ds_read_b128 v[208:211], v169 offset:3072
	ds_read_b128 v[212:215], v169 offset:4096
	ds_read_b128 v[216:219], v169 offset:5120
	ds_read_b128 v[220:223], v169 offset:6144
	ds_read_b128 v[224:227], v169 offset:7168
	global_load_lds_dwordx4 v[164:165], off nt
	v_lshl_add_u64 v[164:165], s[30:31], 0, v[144:145]
	s_add_i32 m0, s39, 0xe000
	s_nop 0
	global_load_lds_dwordx4 v[164:165], off nt
	s_waitcnt vmcnt(8)
	s_waitcnt lgkmcnt(0)
	s_barrier
	s_setprio 1
	s_waitcnt lgkmcnt(0)
	v_mfma_f32_16x16x32_bf16 v[126:129], v[150:153], v[196:199], v[126:129]
	v_mfma_f32_16x16x32_bf16 v[122:125], v[160:163], v[196:199], v[122:125]
	v_mfma_f32_16x16x32_bf16 v[110:113], v[150:153], v[204:207], v[110:113]
	v_mfma_f32_16x16x32_bf16 v[106:109], v[160:163], v[204:207], v[106:109]
	v_mfma_f32_16x16x32_bf16 v[94:97], v[150:153], v[212:215], v[94:97]
	v_mfma_f32_16x16x32_bf16 v[90:93], v[160:163], v[212:215], v[90:93]
	v_mfma_f32_16x16x32_bf16 v[78:81], v[150:153], v[220:223], v[78:81]
	v_mfma_f32_16x16x32_bf16 v[74:77], v[160:163], v[220:223], v[74:77]
	v_mfma_f32_16x16x32_bf16 v[126:129], v[156:159], v[200:203], v[126:129]
	v_mfma_f32_16x16x32_bf16 v[122:125], v[176:179], v[200:203], v[122:125]
	v_mfma_f32_16x16x32_bf16 v[110:113], v[156:159], v[208:211], v[110:113]
	v_mfma_f32_16x16x32_bf16 v[106:109], v[176:179], v[208:211], v[106:109]
	v_mfma_f32_16x16x32_bf16 v[94:97], v[156:159], v[216:219], v[94:97]
	v_mfma_f32_16x16x32_bf16 v[90:93], v[176:179], v[216:219], v[90:93]
	v_mfma_f32_16x16x32_bf16 v[78:81], v[156:159], v[224:227], v[78:81]
	v_mfma_f32_16x16x32_bf16 v[74:77], v[176:179], v[224:227], v[74:77]
	s_setprio 0
	s_setprio 1
	v_mfma_f32_16x16x32_bf16 v[118:121], v[180:183], v[196:199], v[118:121]
	v_mfma_f32_16x16x32_bf16 v[114:117], v[188:191], v[196:199], v[114:117]
	v_mfma_f32_16x16x32_bf16 v[102:105], v[180:183], v[204:207], v[102:105]
	v_mfma_f32_16x16x32_bf16 v[98:101], v[188:191], v[204:207], v[98:101]
	v_mfma_f32_16x16x32_bf16 v[86:89], v[180:183], v[212:215], v[86:89]
	v_mfma_f32_16x16x32_bf16 v[82:85], v[188:191], v[212:215], v[82:85]
	v_mfma_f32_16x16x32_bf16 v[70:73], v[180:183], v[220:223], v[70:73]
	v_mfma_f32_16x16x32_bf16 v[66:69], v[188:191], v[220:223], v[66:69]
	v_mfma_f32_16x16x32_bf16 v[118:121], v[184:187], v[200:203], v[118:121]
	v_mfma_f32_16x16x32_bf16 v[114:117], v[192:195], v[200:203], v[114:117]
	v_mfma_f32_16x16x32_bf16 v[102:105], v[184:187], v[208:211], v[102:105]
	v_mfma_f32_16x16x32_bf16 v[98:101], v[192:195], v[208:211], v[98:101]
	v_mfma_f32_16x16x32_bf16 v[86:89], v[184:187], v[216:219], v[86:89]
	v_mfma_f32_16x16x32_bf16 v[82:85], v[192:195], v[216:219], v[82:85]
	v_mfma_f32_16x16x32_bf16 v[70:73], v[184:187], v[224:227], v[70:73]
	v_mfma_f32_16x16x32_bf16 v[66:69], v[192:195], v[224:227], v[66:69]
	s_setprio 0
	s_barrier
	s_add_i32 s66, s60, s38
	v_lshl_add_u64 v[164:165], s[34:35], 0, v[132:133]
	s_mov_b32 m0, s66
	ds_read_b128 v[196:199], v169 offset:16384
	ds_read_b128 v[200:203], v169 offset:17408
	ds_read_b128 v[204:207], v169 offset:18432
	ds_read_b128 v[208:211], v169 offset:19456
	ds_read_b128 v[212:215], v169 offset:20480
	ds_read_b128 v[216:219], v169 offset:21504
	ds_read_b128 v[220:223], v169 offset:22528
	ds_read_b128 v[224:227], v169 offset:23552
	global_load_lds_dwordx4 v[164:165], off
	s_add_i32 m0, s66, 0x2000
	s_add_u32 s66, s34, 0xb0000
	v_lshl_add_u64 v[228:229], s[34:35], 0, v[136:137]
	s_addc_u32 s67, s35, 0
	s_add_i32 s68, s61, s38
	global_load_lds_dwordx4 v[228:229], off
	v_lshl_add_u64 v[230:231], s[66:67], 0, v[132:133]
	s_mov_b32 m0, s68
	v_lshl_add_u64 v[232:233], s[36:37], 0, v[134:135]
	global_load_lds_dwordx4 v[230:231], off
	v_lshl_add_u64 v[230:231], s[66:67], 0, v[136:137]
	s_add_i32 m0, s68, 0x2000
	s_nop 0
	global_load_lds_dwordx4 v[230:231], off
	v_lshl_add_u64 v[230:231], s[36:37], 0, v[130:131]
	s_mov_b32 m0, s39
	s_nop 0
	global_load_lds_dwordx4 v[230:231], off nt
	s_mov_b32 m0, s40
	s_nop 0
	global_load_lds_dwordx4 v[232:233], off nt
	s_waitcnt vmcnt(8)
	s_waitcnt lgkmcnt(0)
	s_barrier
; #define PG8_STAGE(bufoff, gbase, voff) do { _Pragma("unroll") for (int _i = 0; _i < 2; ++_i) \
;         __builtin_amdgcn_global_load_lds((const unsigned*)((const char*)(gbase) + (voff)[_i]), (PG8_LAS unsigned*)(lds + (bufoff) + ldsw + _i * 8192), 16, 0, 0); } while (0)
; #define PG8_LDA(dst, b, h) do { _Pragma("unroll") for (int m = 0; m < 4; ++m) _Pragma("unroll") for (int k = 0; k < 2; ++k) dst[m][k] = *(const PG8_LAS bf16x8*)(lds + PG8_SA(b, h) + aoff + m * 2048 + k * 1024); } while (0)
; #define PG8_LDB(dst, b, h) do { _Pragma("unroll") for (int n = 0; n < 2; ++n) _Pragma("unroll") for (int k = 0; k < 2; ++k) dst[n][k] = *(const PG8_LAS bf16x8*)(lds + PG8_SB(b, h) + boff + n * 2048 + k * 1024); } while (0)
; #define PG8_MMA(ai, bj, At, Bt) do { __builtin_amdgcn_s_setprio(1); _Pragma("unroll") for (int m = 0; m < 4; ++m) _Pragma("unroll") for (int n = 0; n < 2; ++n) _Pragma("unroll") for (int k = 0; k < 2; ++k) \
;         acc[ai][bj][m][n] = __builtin_amdgcn_mfma_f32_16x16x32_bf16(Bt[n][k], At[m][k], acc[ai][bj][m][n], 0, 0, 0); __builtin_amdgcn_s_setprio(0); } while (0)
; #define PG8_WAIT_V(n) asm volatile("s_waitcnt vmcnt(" #n ")" ::: "memory")
; #define PG8_WAIT_L(n) asm volatile("s_waitcnt lgkmcnt(" #n ")" ::: "memory")
; #define PG8_BAR __builtin_amdgcn_s_barrier()
; #define PG8_SCHED __builtin_amdgcn_sched_barrier(0)
; template <class Epi, class Sched, bool ALIGN_EPI = false, bool SP2 = false, bool AGM = false  >
; __device__ __forceinline__ void gemm_phase(PG8_LAS unsigned char* lds, const Gemm g, const Sched& S, const Epi& E) {
;     ...
;             PG8_WAIT_V(8); PG8_WAIT_L(0); PG8_BAR; PG8_MMA(1, 0, At, B0); PG8_MMA(1, 1, At, B1); PG8_BAR; PG8_SCHED;
;             PG8_LDB(B0, 1, 0); PG8_LDB(B1, 1, 1); PG8_SCHED; PG8_LDA(At, 1, 0); PG8_STAGE(PG8_SA(0, 1), a2 + hstepA, voffA);
;             PG8_WAIT_V(8); PG8_WAIT_L(0); PG8_BAR; PG8_MMA(0, 0, At, B0); PG8_MMA(0, 1, At, B1); PG8_BAR; PG8_SCHED;
;             PG8_LDA(At, 1, 1); PG8_STAGE(PG8_SB(1, 0), b3, voffB); PG8_STAGE(PG8_SB(1, 1), b3 + hstep, voffB); PG8_STAGE(PG8_SA(1, 0), a3, voffA);
	s_setprio 1
	s_waitcnt lgkmcnt(0)
	v_mfma_f32_16x16x32_bf16 v[62:65], v[150:153], v[196:199], v[62:65]
	v_mfma_f32_16x16x32_bf16 v[58:61], v[160:163], v[196:199], v[58:61]
	v_mfma_f32_16x16x32_bf16 v[46:49], v[150:153], v[204:207], v[46:49]
	v_mfma_f32_16x16x32_bf16 v[42:45], v[160:163], v[204:207], v[42:45]
	v_mfma_f32_16x16x32_bf16 v[30:33], v[150:153], v[212:215], v[30:33]
	v_mfma_f32_16x16x32_bf16 v[26:29], v[160:163], v[212:215], v[26:29]
	v_mfma_f32_16x16x32_bf16 v[14:17], v[150:153], v[220:223], v[14:17]
	v_mfma_f32_16x16x32_bf16 v[10:13], v[160:163], v[220:223], v[10:13]
	v_mfma_f32_16x16x32_bf16 v[62:65], v[156:159], v[200:203], v[62:65]
	v_mfma_f32_16x16x32_bf16 v[58:61], v[176:179], v[200:203], v[58:61]
	v_mfma_f32_16x16x32_bf16 v[46:49], v[156:159], v[208:211], v[46:49]
	v_mfma_f32_16x16x32_bf16 v[42:45], v[176:179], v[208:211], v[42:45]
	v_mfma_f32_16x16x32_bf16 v[30:33], v[156:159], v[216:219], v[30:33]
	v_mfma_f32_16x16x32_bf16 v[26:29], v[176:179], v[216:219], v[26:29]
	v_mfma_f32_16x16x32_bf16 v[14:17], v[156:159], v[224:227], v[14:17]
	v_mfma_f32_16x16x32_bf16 v[10:13], v[176:179], v[224:227], v[10:13]
	s_setprio 0
	s_setprio 1
	v_mfma_f32_16x16x32_bf16 v[54:57], v[180:183], v[196:199], v[54:57]
	v_mfma_f32_16x16x32_bf16 v[50:53], v[188:191], v[196:199], v[50:53]
	v_mfma_f32_16x16x32_bf16 v[38:41], v[180:183], v[204:207], v[38:41]
	v_mfma_f32_16x16x32_bf16 v[34:37], v[188:191], v[204:207], v[34:37]
	v_mfma_f32_16x16x32_bf16 v[22:25], v[180:183], v[212:215], v[22:25]
	v_mfma_f32_16x16x32_bf16 v[18:21], v[188:191], v[212:215], v[18:21]
	v_mfma_f32_16x16x32_bf16 v[6:9], v[180:183], v[220:223], v[6:9]
	v_mfma_f32_16x16x32_bf16 v[2:5], v[188:191], v[220:223], v[2:5]
	v_mfma_f32_16x16x32_bf16 v[54:57], v[184:187], v[200:203], v[54:57]
	v_mfma_f32_16x16x32_bf16 v[50:53], v[192:195], v[200:203], v[50:53]
	v_mfma_f32_16x16x32_bf16 v[38:41], v[184:187], v[208:211], v[38:41]
	v_mfma_f32_16x16x32_bf16 v[34:37], v[192:195], v[208:211], v[34:37]
	v_mfma_f32_16x16x32_bf16 v[22:25], v[184:187], v[216:219], v[22:25]
	v_mfma_f32_16x16x32_bf16 v[18:21], v[192:195], v[216:219], v[18:21]
	v_mfma_f32_16x16x32_bf16 v[6:9], v[184:187], v[224:227], v[6:9]
	v_mfma_f32_16x16x32_bf16 v[2:5], v[192:195], v[224:227], v[2:5]
	s_setprio 0
	s_barrier
	s_add_i32 s66, 0, 0x18000
	s_add_i32 s67, 0, 0x1c000
	v_add_u32_e32 v176, s66, v1
	v_add_u32_e32 v192, s67, v1
	ds_read_b128 v[150:153], v176
	ds_read_b128 v[156:159], v176 offset:1024
	ds_read_b128 v[160:163], v176 offset:2048
	ds_read_b128 v[176:179], v176 offset:3072
	ds_read_b128 v[180:183], v192
	ds_read_b128 v[184:187], v192 offset:1024
	ds_read_b128 v[188:191], v192 offset:2048
	ds_read_b128 v[192:195], v192 offset:3072
	s_add_u32 s36, s36, 0xb0000
	s_addc_u32 s37, s37, 0
	s_mov_b32 m0, s41
	v_lshl_add_u64 v[234:235], s[36:37], 0, v[130:131]
	ds_read_b128 v[196:199], v169 offset:32768
	ds_read_b128 v[200:203], v169 offset:33792
	ds_read_b128 v[204:207], v169 offset:34816
	ds_read_b128 v[208:211], v169 offset:35840
	ds_read_b128 v[212:215], v169 offset:36864
	ds_read_b128 v[216:219], v169 offset:37888
	ds_read_b128 v[220:223], v169 offset:38912
	ds_read_b128 v[224:227], v169 offset:39936
	global_load_lds_dwordx4 v[234:235], off nt
	v_lshl_add_u64 v[234:235], s[36:37], 0, v[134:135]
	s_mov_b32 m0, s42
	s_nop 0
	global_load_lds_dwordx4 v[234:235], off nt
	s_waitcnt vmcnt(8)
	s_waitcnt lgkmcnt(0)
	s_barrier
	s_setprio 1
	s_waitcnt lgkmcnt(0)
	v_mfma_f32_16x16x32_bf16 v[126:129], v[150:153], v[196:199], v[126:129]
	v_mfma_f32_16x16x32_bf16 v[122:125], v[160:163], v[196:199], v[122:125]
	v_mfma_f32_16x16x32_bf16 v[110:113], v[150:153], v[204:207], v[110:113]
	v_mfma_f32_16x16x32_bf16 v[106:109], v[160:163], v[204:207], v[106:109]
	v_mfma_f32_16x16x32_bf16 v[94:97], v[150:153], v[212:215], v[94:97]
	v_mfma_f32_16x16x32_bf16 v[90:93], v[160:163], v[212:215], v[90:93]
	v_mfma_f32_16x16x32_bf16 v[78:81], v[150:153], v[220:223], v[78:81]
	v_mfma_f32_16x16x32_bf16 v[74:77], v[160:163], v[220:223], v[74:77]
	v_mfma_f32_16x16x32_bf16 v[126:129], v[156:159], v[200:203], v[126:129]
	v_mfma_f32_16x16x32_bf16 v[122:125], v[176:179], v[200:203], v[122:125]
	v_mfma_f32_16x16x32_bf16 v[110:113], v[156:159], v[208:211], v[110:113]
	v_mfma_f32_16x16x32_bf16 v[106:109], v[176:179], v[208:211], v[106:109]
	v_mfma_f32_16x16x32_bf16 v[94:97], v[156:159], v[216:219], v[94:97]
	v_mfma_f32_16x16x32_bf16 v[90:93], v[176:179], v[216:219], v[90:93]
	v_mfma_f32_16x16x32_bf16 v[78:81], v[156:159], v[224:227], v[78:81]
	v_mfma_f32_16x16x32_bf16 v[74:77], v[176:179], v[224:227], v[74:77]
	s_setprio 0
	s_setprio 1
	v_mfma_f32_16x16x32_bf16 v[118:121], v[180:183], v[196:199], v[118:121]
	v_mfma_f32_16x16x32_bf16 v[114:117], v[188:191], v[196:199], v[114:117]
	v_mfma_f32_16x16x32_bf16 v[102:105], v[180:183], v[204:207], v[102:105]
	v_mfma_f32_16x16x32_bf16 v[98:101], v[188:191], v[204:207], v[98:101]
	v_mfma_f32_16x16x32_bf16 v[86:89], v[180:183], v[212:215], v[86:89]
	v_mfma_f32_16x16x32_bf16 v[82:85], v[188:191], v[212:215], v[82:85]
	v_mfma_f32_16x16x32_bf16 v[70:73], v[180:183], v[220:223], v[70:73]
	v_mfma_f32_16x16x32_bf16 v[66:69], v[188:191], v[220:223], v[66:69]
	v_mfma_f32_16x16x32_bf16 v[118:121], v[184:187], v[200:203], v[118:121]
	v_mfma_f32_16x16x32_bf16 v[114:117], v[192:195], v[200:203], v[114:117]
	v_mfma_f32_16x16x32_bf16 v[102:105], v[184:187], v[208:211], v[102:105]
	v_mfma_f32_16x16x32_bf16 v[98:101], v[192:195], v[208:211], v[98:101]
	v_mfma_f32_16x16x32_bf16 v[86:89], v[184:187], v[216:219], v[86:89]
	v_mfma_f32_16x16x32_bf16 v[82:85], v[192:195], v[216:219], v[82:85]
	v_mfma_f32_16x16x32_bf16 v[70:73], v[184:187], v[224:227], v[70:73]
	v_mfma_f32_16x16x32_bf16 v[66:69], v[192:195], v[224:227], v[66:69]
	s_setprio 0
	s_barrier
; #define PG8_STAGE(bufoff, gbase, voff) do { _Pragma("unroll") for (int _i = 0; _i < 2; ++_i) \
;         __builtin_amdgcn_global_load_lds((const unsigned*)((const char*)(gbase) + (voff)[_i]), (PG8_LAS unsigned*)(lds + (bufoff) + ldsw + _i * 8192), 16, 0, 0); } while (0)
; #define PG8_LDA(dst, b, h) do { _Pragma("unroll") for (int m = 0; m < 4; ++m) _Pragma("unroll") for (int k = 0; k < 2; ++k) dst[m][k] = *(const PG8_LAS bf16x8*)(lds + PG8_SA(b, h) + aoff + m * 2048 + k * 1024); } while (0)
; #define PG8_MMA(ai, bj, At, Bt) do { __builtin_amdgcn_s_setprio(1); _Pragma("unroll") for (int m = 0; m < 4; ++m) _Pragma("unroll") for (int n = 0; n < 2; ++n) _Pragma("unroll") for (int k = 0; k < 2; ++k) \
;         acc[ai][bj][m][n] = __builtin_amdgcn_mfma_f32_16x16x32_bf16(Bt[n][k], At[m][k], acc[ai][bj][m][n], 0, 0, 0); __builtin_amdgcn_s_setprio(0); } while (0)
; #define PG8_WAIT_V(n) asm volatile("s_waitcnt vmcnt(" #n ")" ::: "memory")
; #define PG8_WAIT_L(n) asm volatile("s_waitcnt lgkmcnt(" #n ")" ::: "memory")
; #define PG8_BAR __builtin_amdgcn_s_barrier()
; #define PG8_SCHED __builtin_amdgcn_sched_barrier(0)
; template <class Epi, class Sched, bool ALIGN_EPI = false, bool SP2 = false, bool AGM = false  >
; __device__ __forceinline__ void gemm_phase(PG8_LAS unsigned char* lds, const Gemm g, const Sched& S, const Epi& E) {
;     ...
;         for (int t = 0; t < nt; t += 2) {
;     ...
;             PG8_WAIT_V(8); PG8_WAIT_L(0); PG8_BAR; PG8_MMA(0, 0, At, B0); PG8_MMA(0, 1, At, B1); PG8_BAR; PG8_SCHED;
;             PG8_LDA(At, 1, 1); PG8_STAGE(PG8_SB(1, 0), b3, voffB); PG8_STAGE(PG8_SB(1, 1), b3 + hstep, voffB); PG8_STAGE(PG8_SA(1, 0), a3, voffA);
;             PG8_WAIT_V(8); PG8_WAIT_L(0); PG8_BAR; PG8_MMA(1, 0, At, B0); PG8_MMA(1, 1, At, B1); PG8_BAR; PG8_SCHED;
	s_add_i32 s36, s66, s38
	v_lshl_add_u64 v[164:165], v[164:165], 0, s[24:25]
	s_mov_b32 m0, s36
	ds_read_b128 v[196:199], v169 offset:49152
	ds_read_b128 v[200:203], v169 offset:50176
	ds_read_b128 v[204:207], v169 offset:51200
	ds_read_b128 v[208:211], v169 offset:52224
	ds_read_b128 v[212:215], v169 offset:53248
	ds_read_b128 v[216:219], v169 offset:54272
	ds_read_b128 v[220:223], v169 offset:55296
	ds_read_b128 v[224:227], v169 offset:56320
	global_load_lds_dwordx4 v[164:165], off
	s_add_i32 m0, s36, 0x2000
	s_add_u32 s34, s34, 0xb0080
	v_lshl_add_u64 v[164:165], v[228:229], 0, s[24:25]
	s_addc_u32 s35, s35, 0
	s_add_i32 s36, s67, s38
	global_load_lds_dwordx4 v[164:165], off
	v_lshl_add_u64 v[164:165], s[34:35], 0, v[132:133]
	s_mov_b32 m0, s36
	s_nop 0
	global_load_lds_dwordx4 v[164:165], off
	v_lshl_add_u64 v[164:165], s[34:35], 0, v[136:137]
	s_add_i32 m0, s36, 0x2000
	s_nop 0
	global_load_lds_dwordx4 v[164:165], off
	v_lshl_add_u64 v[164:165], v[230:231], 0, s[24:25]
	s_mov_b32 m0, s55
	s_nop 0
	global_load_lds_dwordx4 v[164:165], off nt
	v_lshl_add_u64 v[164:165], v[232:233], 0, s[24:25]
	s_mov_b32 m0, s58
	s_nop 0
	global_load_lds_dwordx4 v[164:165], off nt
	s_waitcnt vmcnt(8)
	s_waitcnt lgkmcnt(0)
	s_barrier
	s_setprio 1
	s_waitcnt lgkmcnt(0)
	v_mfma_f32_16x16x32_bf16 v[62:65], v[150:153], v[196:199], v[62:65]
	v_mfma_f32_16x16x32_bf16 v[58:61], v[160:163], v[196:199], v[58:61]
	v_mfma_f32_16x16x32_bf16 v[46:49], v[150:153], v[204:207], v[46:49]
	v_mfma_f32_16x16x32_bf16 v[42:45], v[160:163], v[204:207], v[42:45]
	v_mfma_f32_16x16x32_bf16 v[30:33], v[150:153], v[212:215], v[30:33]
	v_mfma_f32_16x16x32_bf16 v[26:29], v[160:163], v[212:215], v[26:29]
	v_mfma_f32_16x16x32_bf16 v[14:17], v[150:153], v[220:223], v[14:17]
	v_mfma_f32_16x16x32_bf16 v[10:13], v[160:163], v[220:223], v[10:13]
	v_mfma_f32_16x16x32_bf16 v[62:65], v[156:159], v[200:203], v[62:65]
	v_mfma_f32_16x16x32_bf16 v[58:61], v[176:179], v[200:203], v[58:61]
	v_mfma_f32_16x16x32_bf16 v[46:49], v[156:159], v[208:211], v[46:49]
	v_mfma_f32_16x16x32_bf16 v[42:45], v[176:179], v[208:211], v[42:45]
	v_mfma_f32_16x16x32_bf16 v[30:33], v[156:159], v[216:219], v[30:33]
	v_mfma_f32_16x16x32_bf16 v[26:29], v[176:179], v[216:219], v[26:29]
	v_mfma_f32_16x16x32_bf16 v[14:17], v[156:159], v[224:227], v[14:17]
	v_mfma_f32_16x16x32_bf16 v[10:13], v[176:179], v[224:227], v[10:13]
	s_setprio 0
	s_setprio 1
	v_mfma_f32_16x16x32_bf16 v[54:57], v[180:183], v[196:199], v[54:57]
	v_mfma_f32_16x16x32_bf16 v[50:53], v[188:191], v[196:199], v[50:53]
	v_mfma_f32_16x16x32_bf16 v[38:41], v[180:183], v[204:207], v[38:41]
	v_mfma_f32_16x16x32_bf16 v[34:37], v[188:191], v[204:207], v[34:37]
	v_mfma_f32_16x16x32_bf16 v[22:25], v[180:183], v[212:215], v[22:25]
	v_mfma_f32_16x16x32_bf16 v[18:21], v[188:191], v[212:215], v[18:21]
	v_mfma_f32_16x16x32_bf16 v[6:9], v[180:183], v[220:223], v[6:9]
	v_mfma_f32_16x16x32_bf16 v[2:5], v[188:191], v[220:223], v[2:5]
	v_mfma_f32_16x16x32_bf16 v[54:57], v[184:187], v[200:203], v[54:57]
	v_mfma_f32_16x16x32_bf16 v[50:53], v[192:195], v[200:203], v[50:53]
	v_mfma_f32_16x16x32_bf16 v[38:41], v[184:187], v[208:211], v[38:41]
	v_mfma_f32_16x16x32_bf16 v[34:37], v[192:195], v[208:211], v[34:37]
	v_mfma_f32_16x16x32_bf16 v[22:25], v[184:187], v[216:219], v[22:25]
	v_mfma_f32_16x16x32_bf16 v[18:21], v[192:195], v[216:219], v[18:21]
	v_mfma_f32_16x16x32_bf16 v[6:9], v[184:187], v[224:227], v[6:9]
	v_mfma_f32_16x16x32_bf16 v[2:5], v[192:195], v[224:227], v[2:5]
	s_setprio 0
	s_barrier
	s_add_i32 s65, s65, 2
	s_add_u32 s30, s30, 0x100
	s_addc_u32 s31, s31, 0
	s_add_u32 s5, s5, 0x100
	s_addc_u32 s33, s33, 0
	s_cmp_gt_u32 s65, 41
	s_cbranch_scc0 .LBB0_1068
	s_and_b64 vcc, exec, s[26:27]
	s_cbranch_vccz .LBB0_1071
	s_barrier
